# attention main loop: K/V LDS staging and next-tile global prefetch moved into the shadow of the first ten QK MFMAs
# baseline (speedup 1.0000x reference)
; #define LAS __attribute__((address_space(3)))
; __device__ __forceinline__ void attn_unit(const bf16* QB, const bf16* KN, const bf16* KR, const bf16* VT, bf16* YC, LAS unsigned char* lds, int b, int h, int u, int tid, int lane, int wave) {
;     ...
;     for (int kt = 0; kt < nt_unit; ++kt) {
;         if (kt + 1 < nt_unit) { LAS unsigned char* nx = lds + ((kt + 1) & 1) * AT_STAGE;
; #pragma unroll
;             for (int i = 0; i < 2; ++i) { *(LAS u32x4*)(nx + kndst[i]) = kreg[i]; *(LAS u32x4*)(nx + vtdst[i]) = vreg[i]; }
;             *(LAS u32x4*)(nx + krdst) = kreg[2];
;             if (kt + 2 < nt_unit) { const unsigned t2 = (unsigned)(kt + 2) * 64u;
; #pragma unroll
;                 for (int i = 0; i < 2; ++i) { kreg[i] = *(const u32x4*)(KN + (knoff[i] + t2 * 512u)); vreg[i] = *(const u32x4*)(VT + (vtoff[i] + t2)); }
;                 kreg[2] = *(const u32x4*)(KR + (kroff + t2 * 64u)); }
;         }
;         LAS unsigned char* st = lds + (kt & 1) * AT_STAGE;
;         if (kt < nt_wave) {
;             f32x16 sa[2];
; #pragma unroll
;             for (int mt = 0; mt < 2; ++mt) {
; #pragma unroll
;                 for (int i = 0; i < 16; ++i) sa[mt][i] = 0.f;
; #pragma unroll
;                 for (int ks = 0; ks < 12; ++ks) { const bf16x8 af = *(const LAS bf16x8*)(st + (32 * mt + r32) * AT_KSTR + 32 * ks + 16 * hi);
;                     sa[mt] = __builtin_amdgcn_mfma_f32_32x32x16_bf16(af, qf[ks], sa[mt], 0, 0, 0); }
;             }
;             float mx = sa[0][0];
; #pragma unroll
;             for (int i = 1; i < 16; ++i) mx = fmaxf(mx, sa[0][i]);
; #pragma unroll
;             for (int i = 0; i < 16; ++i) mx = fmaxf(mx, sa[1][i]);
;             mx = fmaxf(mx, __shfl_xor(mx, 32));
;             const bool grow = __builtin_amdgcn_ballot_w64(mx - m_run > 8.0f) != 0ull;
;             const float m_new = grow ? fmaxf(m_run, mx) : m_run; const float alpha = grow ? __builtin_amdgcn_exp2f(m_run - m_new) : 1.0f; m_run = m_new;
.LBB0_1470:
	s_add_i32 s6, s4, 1
	s_bitcmp1_b32 s6, 0
	s_cselect_b32 s5, 0xac00, 0
	s_add_i32 s28, s5, 0
	s_cmp_gt_i32 s4, s0
	s_cbranch_scc1 .Lattn_stage_only
	s_bitcmp1_b32 s4, 0
	s_cselect_b32 s4, 0xac00, 0
	v_add_u32_e32 v208, s4, v199
	v_add_u32_e32 v72, v208, v194
	v_add_u32_e32 v230, v208, v195
	ds_read_b128 v[210:213], v72
	ds_read_b128 v[214:217], v72 offset:32
	ds_read_b128 v[218:221], v72 offset:64
	ds_read_b128 v[222:225], v72 offset:96
	s_waitcnt lgkmcnt(3)
	v_mfma_f32_32x32x16_bf16 v[80:95], v[210:213], v[140:143], 0
	ds_read_b128 v[226:229], v72 offset:128
	v_add_u32_e32 v64, s28, v170
	s_waitcnt vmcnt(4)
	ds_write_b128 v64, v[148:151]
	s_waitcnt lgkmcnt(4)
	v_mfma_f32_32x32x16_bf16 v[80:95], v[214:217], v[136:139], v[80:95]
	ds_read_b128 v[210:213], v72 offset:160
	v_add_u32_e32 v64, s28, v174
	s_waitcnt vmcnt(3)
	ds_write_b128 v64, v[144:147] offset:25600
	s_waitcnt lgkmcnt(5)
	v_mfma_f32_32x32x16_bf16 v[80:95], v[218:221], v[132:135], v[80:95]
	ds_read_b128 v[214:217], v72 offset:192
	v_add_u32_e32 v64, s28, v172
	s_waitcnt vmcnt(2)
	ds_write_b128 v64, v[156:159]
	s_waitcnt lgkmcnt(6)
	v_mfma_f32_32x32x16_bf16 v[80:95], v[222:225], v[128:131], v[80:95]
	ds_read_b128 v[218:221], v72 offset:224
	v_add_u32_e32 v64, s28, v176
	s_waitcnt vmcnt(1)
	ds_write_b128 v64, v[152:155] offset:25600
	s_waitcnt lgkmcnt(7)
	v_mfma_f32_32x32x16_bf16 v[80:95], v[226:229], v[124:127], v[80:95]
	ds_read_b128 v[222:225], v72 offset:256
	v_add_u32_e32 v64, s28, v192
	s_waitcnt vmcnt(0)
	ds_write_b128 v64, v[160:163] offset:256
	s_waitcnt lgkmcnt(7)
	v_mfma_f32_32x32x16_bf16 v[80:95], v[210:213], v[120:123], v[80:95]
	ds_read_b128 v[226:229], v72 offset:288
	v_lshl_add_u64 v[64:65], v[168:169], 1, s[62:63]
	global_load_dwordx4 v[148:151], v[64:65], off
	s_waitcnt lgkmcnt(6)
	v_mfma_f32_32x32x16_bf16 v[80:95], v[214:217], v[116:119], v[80:95]
	ds_read_b128 v[210:213], v72 offset:320
	v_add_u32_e32 v66, v188, v207
	v_mov_b32_e32 v67, v169
	v_lshl_add_u64 v[66:67], v[66:67], 1, s[48:49]
	global_load_dwordx4 v[144:147], v[66:67], off
	s_waitcnt lgkmcnt(5)
	v_mfma_f32_32x32x16_bf16 v[80:95], v[218:221], v[112:115], v[80:95]
	ds_read_b128 v[214:217], v72 offset:352
	v_mov_b32_e32 v185, v169
	v_lshl_add_u64 v[64:65], v[184:185], 1, s[62:63]
	global_load_dwordx4 v[156:159], v[64:65], off
	s_waitcnt lgkmcnt(4)
	v_mfma_f32_32x32x16_bf16 v[80:95], v[222:225], v[108:111], v[80:95]
	ds_read_b128 v[218:221], v230
	v_add_u32_e32 v66, v188, v206
	v_mov_b32_e32 v67, v169
	v_lshl_add_u64 v[66:67], v[66:67], 1, s[48:49]
	global_load_dwordx4 v[152:155], v[66:67], off
	s_waitcnt lgkmcnt(3)
	v_mfma_f32_32x32x16_bf16 v[80:95], v[226:229], v[104:107], v[80:95]
	ds_read_b128 v[222:225], v230 offset:32
	v_add_u32_e32 v64, v188, v181
	v_mov_b32_e32 v65, v169
	v_lshl_add_u64 v[64:65], v[64:65], 1, s[54:55]
	global_load_dwordx4 v[160:163], v[64:65], off
	s_waitcnt lgkmcnt(3)
	v_mfma_f32_32x32x16_bf16 v[80:95], v[210:213], v[100:103], v[80:95]
	ds_read_b128 v[226:229], v230 offset:64
	s_waitcnt lgkmcnt(3)
	v_mfma_f32_32x32x16_bf16 v[80:95], v[214:217], v[96:99], v[80:95]
	ds_read_b128 v[210:213], v230 offset:96
	s_waitcnt lgkmcnt(3)
	v_mfma_f32_32x32x16_bf16 v[64:79], v[218:221], v[140:143], 0
	ds_read_b128 v[214:217], v230 offset:128
	s_waitcnt lgkmcnt(3)
	v_mfma_f32_32x32x16_bf16 v[64:79], v[222:225], v[136:139], v[64:79]
	ds_read_b128 v[218:221], v230 offset:160
	s_waitcnt lgkmcnt(3)
	v_mfma_f32_32x32x16_bf16 v[64:79], v[226:229], v[132:135], v[64:79]
	ds_read_b128 v[222:225], v230 offset:192
	s_waitcnt lgkmcnt(3)
	v_mfma_f32_32x32x16_bf16 v[64:79], v[210:213], v[128:131], v[64:79]
	ds_read_b128 v[226:229], v230 offset:224
	s_waitcnt lgkmcnt(3)
	v_mfma_f32_32x32x16_bf16 v[64:79], v[214:217], v[124:127], v[64:79]
	ds_read_b128 v[210:213], v230 offset:256
	v_max_f32_e32 v209, v80, v81
	v_max3_f32 v209, v209, v82, v83
	s_waitcnt lgkmcnt(3)
	v_mfma_f32_32x32x16_bf16 v[64:79], v[218:221], v[120:123], v[64:79]
	ds_read_b128 v[214:217], v230 offset:288
	v_max3_f32 v209, v209, v84, v85
	s_waitcnt lgkmcnt(3)
	v_mfma_f32_32x32x16_bf16 v[64:79], v[222:225], v[116:119], v[64:79]
	ds_read_b128 v[218:221], v230 offset:320
	v_max3_f32 v209, v209, v86, v87
	s_waitcnt lgkmcnt(3)
	v_mfma_f32_32x32x16_bf16 v[64:79], v[226:229], v[112:115], v[64:79]
	ds_read_b128 v[222:225], v230 offset:352
	v_max3_f32 v209, v209, v88, v89
	s_waitcnt lgkmcnt(3)
	v_mfma_f32_32x32x16_bf16 v[64:79], v[210:213], v[108:111], v[64:79]
	v_max3_f32 v209, v209, v90, v91
	v_and_b32_e32 v226, 64, v167
	s_waitcnt lgkmcnt(2)
	v_mfma_f32_32x32x16_bf16 v[64:79], v[214:217], v[104:107], v[64:79]
	v_max3_f32 v209, v209, v92, v93
	v_xor_b32_e32 v227, 32, v167
	s_waitcnt lgkmcnt(1)
	v_mfma_f32_32x32x16_bf16 v[64:79], v[218:221], v[100:103], v[64:79]
	v_max3_f32 v209, v209, v94, v95
	v_add_u32_e32 v226, 64, v226
	s_waitcnt lgkmcnt(0)
	v_mfma_f32_32x32x16_bf16 v[64:79], v[222:225], v[96:99], v[64:79]
	v_cmp_lt_i32_e32 vcc, v227, v226
	s_nop 1
	v_cndmask_b32_e32 v227, v167, v227, vcc
	v_lshlrev_b32_e32 v227, 2, v227
	s_nop 7
	v_max3_f32 v185, v209, v64, v65
	v_max3_f32 v185, v185, v66, v67
	v_max3_f32 v185, v185, v68, v69
	v_max3_f32 v185, v185, v70, v71
	v_max3_f32 v185, v185, v72, v73
	v_max3_f32 v185, v185, v74, v75
	v_max3_f32 v185, v185, v76, v77
	v_max3_f32 v185, v185, v78, v79
	ds_bpermute_b32 v209, v227, v185
	s_waitcnt lgkmcnt(0)
	v_max_f32_e32 v209, v209, v209
	v_max_f32_e32 v185, v185, v209
	v_sub_f32_e32 v209, v185, v186
	v_cmp_lt_f32_e32 vcc, s72, v209
	s_cmp_eq_u64 vcc, 0
	v_max_f32_e32 v209, v186, v186
	v_max_f32_e32 v185, v209, v185
	s_cselect_b64 s[4:5], -1, 0
	v_cndmask_b32_e64 v185, v185, v186, s[4:5]
	v_sub_f32_e32 v186, v186, v185
	v_exp_f32_e32 v186, v186
	s_and_b64 vcc, exec, s[4:5]
	s_cbranch_vccnz .LBB0_1473
; __device__ __forceinline__ void attn_unit(const bf16* QB, const bf16* KN, const bf16* KR, const bf16* VT, bf16* YC, LAS unsigned char* lds, int b, int h, int u, int tid, int lane, int wave) {
;     ...
;             if (grow) {
; #pragma unroll
;                 for (int d = 0; d < 4; ++d)
; #pragma unroll
;                     for (int i = 0; i < 16; ++i) ot[d][i] *= alpha;
;             }
	v_pk_mul_f32 v[62:63], v[62:63], v[186:187] op_sel_hi:[1,0]
	v_pk_mul_f32 v[60:61], v[60:61], v[186:187] op_sel_hi:[1,0]
	v_pk_mul_f32 v[58:59], v[58:59], v[186:187] op_sel_hi:[1,0]
	v_pk_mul_f32 v[56:57], v[56:57], v[186:187] op_sel_hi:[1,0]
	v_pk_mul_f32 v[54:55], v[54:55], v[186:187] op_sel_hi:[1,0]
	v_pk_mul_f32 v[52:53], v[52:53], v[186:187] op_sel_hi:[1,0]
	v_pk_mul_f32 v[50:51], v[50:51], v[186:187] op_sel_hi:[1,0]
	v_pk_mul_f32 v[48:49], v[48:49], v[186:187] op_sel_hi:[1,0]
	v_pk_mul_f32 v[46:47], v[46:47], v[186:187] op_sel_hi:[1,0]
	v_pk_mul_f32 v[44:45], v[44:45], v[186:187] op_sel_hi:[1,0]
	v_pk_mul_f32 v[42:43], v[42:43], v[186:187] op_sel_hi:[1,0]
	v_pk_mul_f32 v[40:41], v[40:41], v[186:187] op_sel_hi:[1,0]
	v_pk_mul_f32 v[38:39], v[38:39], v[186:187] op_sel_hi:[1,0]
	v_pk_mul_f32 v[36:37], v[36:37], v[186:187] op_sel_hi:[1,0]
	v_pk_mul_f32 v[34:35], v[34:35], v[186:187] op_sel_hi:[1,0]
	v_pk_mul_f32 v[32:33], v[32:33], v[186:187] op_sel_hi:[1,0]
	v_pk_mul_f32 v[30:31], v[30:31], v[186:187] op_sel_hi:[1,0]
	v_pk_mul_f32 v[28:29], v[28:29], v[186:187] op_sel_hi:[1,0]
	v_pk_mul_f32 v[26:27], v[26:27], v[186:187] op_sel_hi:[1,0]
	v_pk_mul_f32 v[24:25], v[24:25], v[186:187] op_sel_hi:[1,0]
	v_pk_mul_f32 v[22:23], v[22:23], v[186:187] op_sel_hi:[1,0]
	v_pk_mul_f32 v[20:21], v[20:21], v[186:187] op_sel_hi:[1,0]
	v_pk_mul_f32 v[18:19], v[18:19], v[186:187] op_sel_hi:[1,0]
	v_pk_mul_f32 v[16:17], v[16:17], v[186:187] op_sel_hi:[1,0]
	v_pk_mul_f32 v[14:15], v[14:15], v[186:187] op_sel_hi:[1,0]
	v_pk_mul_f32 v[12:13], v[12:13], v[186:187] op_sel_hi:[1,0]
	v_pk_mul_f32 v[10:11], v[10:11], v[186:187] op_sel_hi:[1,0]
	v_pk_mul_f32 v[8:9], v[8:9], v[186:187] op_sel_hi:[1,0]
	v_pk_mul_f32 v[6:7], v[6:7], v[186:187] op_sel_hi:[1,0]
	v_pk_mul_f32 v[4:5], v[4:5], v[186:187] op_sel_hi:[1,0]
	v_pk_mul_f32 v[2:3], v[2:3], v[186:187] op_sel_hi:[1,0]
	v_pk_mul_f32 v[0:1], v[0:1], v[186:187] op_sel_hi:[1,0]

; #define LAS __attribute__((address_space(3)))
; __device__ __forceinline__ void attn_unit(const bf16* QB, const bf16* KN, const bf16* KR, const bf16* VT, bf16* YC, LAS unsigned char* lds, int b, int h, int u, int tid, int lane, int wave) {
;     ...
;         if (kt + 1 < nt_unit) { LAS unsigned char* nx = lds + ((kt + 1) & 1) * AT_STAGE;
; #pragma unroll
;             for (int i = 0; i < 2; ++i) { *(LAS u32x4*)(nx + kndst[i]) = kreg[i]; *(LAS u32x4*)(nx + vtdst[i]) = vreg[i]; }
;             *(LAS u32x4*)(nx + krdst) = kreg[2];
;             if (kt + 2 < nt_unit) { const unsigned t2 = (unsigned)(kt + 2) * 64u;
; #pragma unroll
;                 for (int i = 0; i < 2; ++i) { kreg[i] = *(const u32x4*)(KN + (knoff[i] + t2 * 512u)); vreg[i] = *(const u32x4*)(VT + (vtoff[i] + t2)); }
;                 kreg[2] = *(const u32x4*)(KR + (kroff + t2 * 64u)); }
;         }
.Lattn_stage_only:
	v_add_u32_e32 v64, s28, v170
	s_waitcnt vmcnt(4)
	ds_write_b128 v64, v[148:151]
	v_add_u32_e32 v64, s28, v174
	s_waitcnt vmcnt(3)
	ds_write_b128 v64, v[144:147] offset:25600
	v_add_u32_e32 v64, s28, v172
	s_waitcnt vmcnt(2)
	ds_write_b128 v64, v[156:159]
	v_add_u32_e32 v64, s28, v176
	s_waitcnt vmcnt(1)
	ds_write_b128 v64, v[152:155] offset:25600
	v_add_u32_e32 v64, s28, v192
	v_add_u32_e32 v66, v188, v207
	v_mov_b32_e32 v67, v169
	s_waitcnt vmcnt(0)
	ds_write_b128 v64, v[160:163] offset:256
	v_lshl_add_u64 v[64:65], v[168:169], 1, s[62:63]
	v_lshl_add_u64 v[66:67], v[66:67], 1, s[48:49]
	v_mov_b32_e32 v185, v169
	global_load_dwordx4 v[148:151], v[64:65], off
	global_load_dwordx4 v[144:147], v[66:67], off
	v_lshl_add_u64 v[64:65], v[184:185], 1, s[62:63]
	v_add_u32_e32 v66, v188, v206
	v_mov_b32_e32 v67, v169
	v_lshl_add_u64 v[66:67], v[66:67], 1, s[48:49]
	global_load_dwordx4 v[156:159], v[64:65], off
	global_load_dwordx4 v[152:155], v[66:67], off
	v_add_u32_e32 v64, v188, v181
	v_mov_b32_e32 v65, v169
	v_lshl_add_u64 v[64:65], v[64:65], 1, s[54:55]
	global_load_dwordx4 v[160:163], v[64:65], off
